# attention loop row sums: 32 v_pk_add_f32 per key tile split into scalar v_add_f32 pairs (bit-identical), on top of the static priority raise version
# speedup vs baseline: 1.0099x; 1.0033x over previous
.Lag_nobar_b:
	s_nop 7
	s_nop 1
	v_exp_f32_e32 v112, v112
	v_exp_f32_e32 v113, v113
	v_exp_f32_e32 v114, v114
	v_exp_f32_e32 v115, v115
	v_exp_f32_e32 v116, v116
	v_exp_f32_e32 v117, v117
	v_exp_f32_e32 v118, v118
	v_exp_f32_e32 v119, v119
	v_exp_f32_e32 v120, v120
	v_exp_f32_e32 v121, v121
	v_exp_f32_e32 v122, v122
	v_exp_f32_e32 v123, v123
	v_exp_f32_e32 v124, v124
	v_exp_f32_e32 v125, v125
	v_exp_f32_e32 v126, v126
	v_exp_f32_e32 v127, v127
	v_exp_f32_e32 v80, v80
	v_exp_f32_e32 v81, v81
	v_exp_f32_e32 v82, v82
	v_exp_f32_e32 v83, v83
	v_exp_f32_e32 v84, v84
	v_exp_f32_e32 v85, v85
	v_exp_f32_e32 v86, v86
	v_exp_f32_e32 v87, v87
	v_exp_f32_e32 v88, v88
	v_exp_f32_e32 v89, v89
	v_exp_f32_e32 v90, v90
	v_exp_f32_e32 v91, v91
	v_exp_f32_e32 v92, v92
	v_exp_f32_e32 v93, v93
	v_exp_f32_e32 v94, v94
	v_exp_f32_e32 v95, v95
	v_add_f32_e32 v186, v186, v112
	v_add_f32_e32 v187, v187, v113
	v_cvt_pk_bf16_f32 v112, v112, v113
	v_add_f32_e32 v186, v186, v114
	v_add_f32_e32 v187, v187, v115
	v_cvt_pk_bf16_f32 v113, v114, v115
	v_add_f32_e32 v186, v186, v116
	v_add_f32_e32 v187, v187, v117
	v_cvt_pk_bf16_f32 v114, v116, v117
	v_add_f32_e32 v186, v186, v118
	v_add_f32_e32 v187, v187, v119
	v_cvt_pk_bf16_f32 v115, v118, v119
	v_add_f32_e32 v186, v186, v120
	v_add_f32_e32 v187, v187, v121
	v_cvt_pk_bf16_f32 v116, v120, v121
	v_add_f32_e32 v186, v186, v122
	v_add_f32_e32 v187, v187, v123
	v_cvt_pk_bf16_f32 v117, v122, v123
	v_add_f32_e32 v186, v186, v124
	v_add_f32_e32 v187, v187, v125
	v_cvt_pk_bf16_f32 v118, v124, v125
	v_add_f32_e32 v186, v186, v126
	v_add_f32_e32 v187, v187, v127
	v_cvt_pk_bf16_f32 v119, v126, v127
	v_exp_f32_e32 v128, v128
	v_exp_f32_e32 v129, v129
	v_exp_f32_e32 v130, v130
	v_exp_f32_e32 v131, v131
	v_exp_f32_e32 v132, v132
	v_exp_f32_e32 v133, v133
	v_exp_f32_e32 v134, v134
	v_exp_f32_e32 v135, v135
	v_exp_f32_e32 v136, v136
	v_exp_f32_e32 v137, v137
	v_exp_f32_e32 v138, v138
	v_exp_f32_e32 v139, v139
	v_exp_f32_e32 v140, v140
	v_exp_f32_e32 v141, v141
	v_exp_f32_e32 v142, v142
	v_exp_f32_e32 v143, v143
	v_add_f32_e32 v188, v188, v80
	v_add_f32_e32 v189, v189, v81
	v_cvt_pk_bf16_f32 v80, v80, v81
	v_add_f32_e32 v188, v188, v82
	v_add_f32_e32 v189, v189, v83
	v_cvt_pk_bf16_f32 v81, v82, v83
	v_add_f32_e32 v188, v188, v84
	v_add_f32_e32 v189, v189, v85
	v_cvt_pk_bf16_f32 v82, v84, v85
	v_add_f32_e32 v188, v188, v86
	v_add_f32_e32 v189, v189, v87
	v_cvt_pk_bf16_f32 v83, v86, v87
	v_add_f32_e32 v188, v188, v88
	v_add_f32_e32 v189, v189, v89
	v_cvt_pk_bf16_f32 v84, v88, v89
	v_add_f32_e32 v188, v188, v90
	v_add_f32_e32 v189, v189, v91
	v_cvt_pk_bf16_f32 v85, v90, v91
	v_add_f32_e32 v188, v188, v92
	v_add_f32_e32 v189, v189, v93
	v_cvt_pk_bf16_f32 v86, v92, v93
	v_add_f32_e32 v188, v188, v94
	v_add_f32_e32 v189, v189, v95
	v_cvt_pk_bf16_f32 v87, v94, v95
	v_exp_f32_e32 v96, v96
	v_exp_f32_e32 v97, v97
	v_exp_f32_e32 v98, v98
	v_exp_f32_e32 v99, v99
	v_exp_f32_e32 v100, v100
	v_exp_f32_e32 v101, v101
	v_exp_f32_e32 v102, v102
	v_exp_f32_e32 v103, v103
	v_exp_f32_e32 v104, v104
	v_exp_f32_e32 v105, v105
	v_exp_f32_e32 v106, v106
	v_exp_f32_e32 v107, v107
	v_exp_f32_e32 v108, v108
	v_exp_f32_e32 v109, v109
	v_exp_f32_e32 v110, v110
	v_exp_f32_e32 v111, v111
	v_add_f32_e32 v186, v186, v128
	v_add_f32_e32 v187, v187, v129
	v_cvt_pk_bf16_f32 v128, v128, v129
	v_add_f32_e32 v186, v186, v130
	v_add_f32_e32 v187, v187, v131
	v_cvt_pk_bf16_f32 v129, v130, v131
	v_add_f32_e32 v186, v186, v132
	v_add_f32_e32 v187, v187, v133
	v_cvt_pk_bf16_f32 v130, v132, v133
	v_add_f32_e32 v186, v186, v134
	v_add_f32_e32 v187, v187, v135
	v_cvt_pk_bf16_f32 v131, v134, v135
	v_add_f32_e32 v186, v186, v136
	v_add_f32_e32 v187, v187, v137
	v_cvt_pk_bf16_f32 v132, v136, v137
	v_add_f32_e32 v186, v186, v138
	v_add_f32_e32 v187, v187, v139
	v_cvt_pk_bf16_f32 v133, v138, v139
	v_add_f32_e32 v186, v186, v140
	v_add_f32_e32 v187, v187, v141
	v_cvt_pk_bf16_f32 v134, v140, v141
	v_add_f32_e32 v186, v186, v142
	v_add_f32_e32 v187, v187, v143
	v_cvt_pk_bf16_f32 v135, v142, v143
	v_add_f32_e32 v188, v188, v96
	v_add_f32_e32 v189, v189, v97
	v_cvt_pk_bf16_f32 v96, v96, v97
	v_add_f32_e32 v188, v188, v98
	v_add_f32_e32 v189, v189, v99
	v_cvt_pk_bf16_f32 v97, v98, v99
	v_add_f32_e32 v188, v188, v100
	v_add_f32_e32 v189, v189, v101
	v_cvt_pk_bf16_f32 v98, v100, v101
	v_add_f32_e32 v188, v188, v102
	v_add_f32_e32 v189, v189, v103
	v_cvt_pk_bf16_f32 v99, v102, v103
	v_add_f32_e32 v188, v188, v104
	v_add_f32_e32 v189, v189, v105
	v_cvt_pk_bf16_f32 v100, v104, v105
	v_add_f32_e32 v188, v188, v106
	v_add_f32_e32 v189, v189, v107
	v_cvt_pk_bf16_f32 v101, v106, v107
	v_add_f32_e32 v188, v188, v108
	v_add_f32_e32 v189, v189, v109
	v_cvt_pk_bf16_f32 v102, v108, v109
	v_add_f32_e32 v188, v188, v110
	v_add_f32_e32 v189, v189, v111
	v_cvt_pk_bf16_f32 v103, v110, v111
	s_cmp_lt_u32 s33, 0x100
	s_cbranch_scc0 .Lag_nobar_a
	s_barrier
